# speedup vs baseline: 1.0046x; 1.0046x over previous
; __device__ __forceinline__ float siluf_(float x) { return x * __builtin_amdgcn_rcpf(1.0f + __builtin_amdgcn_exp2f(-1.4426950408889634f * x)); }
;     ...
;     } else if constexpr (EPI == EPI_SWIGLU) {
;       u16* Gp = (u16*)(ws + OFF_G);
; #pragma unroll
;       for (int m = 0; m < MT; ++m)
; #pragma unroll
;         for (int h = 0; h < 2; ++h) {
;           u32x2 pk;
;           pk.x = pack2(siluf_(acc[m][h][0]) * acc[m][2 + h][0], siluf_(acc[m][h][1]) * acc[m][2 + h][1]);
;           pk.y = pack2(siluf_(acc[m][h][2]) * acc[m][2 + h][2], siluf_(acc[m][h][3]) * acc[m][2 + h][3]);
;           *(u32x2*)(Gp + (size_t)(rbase + m * 16) * DFF + pn * 128 + wc * 32 + h * 16 + fq * 4) = pk;
;         }
.LBB0_182:
	v_mfma_f32_16x16x32_bf16 v[44:47], v[156:159], v[28:31], v[52:55]
	v_mfma_f32_16x16x32_bf16 v[52:55], v[160:163], v[28:31], v[168:171]
	v_mfma_f32_16x16x32_bf16 v[40:43], v[164:167], v[28:31], v[40:43]
	v_mfma_f32_16x16x32_bf16 v[36:39], v[152:155], v[176:179], v[36:39]
	v_mfma_f32_16x16x32_bf16 v[28:31], v[156:159], v[176:179], v[32:35]
	v_mfma_f32_16x16x32_bf16 v[32:35], v[160:163], v[176:179], v[172:175]
	v_mfma_f32_16x16x32_bf16 v[24:27], v[164:167], v[176:179], v[24:27]
	s_lshl_b32 s0, s25, 7
	s_ashr_i32 s1, s0, 31
	v_lshl_add_u32 v154, s50, 8, v223
	v_lshl_add_u64 v[152:153], s[0:1], 1, v[216:217]
	v_mad_i64_i32 v[156:157], s[0:1], v154, s53, v[152:153]
	s_mov_b32 s98, 0x16000
	s_mov_b32 s99, 0
	s_mov_b32 s100, 0xbfb8aa3b
	s_mov_b32 s101, 0xbfb8aa3b
	v_bfe_u32 v154, v228, 4, 1
	v_mul_u32_u24_e32 v154, 24, v154
	v_mov_b32_e32 v155, 0
	v_lshl_add_u64 v[156:157], v[156:157], 0, v[154:155]
	v_mul_f32_e32 v152, 0xbfb8aa3b, v144
	v_mul_f32_e32 v153, 0xbfb8aa3b, v145
	v_mul_f32_e32 v154, 0xbfb8aa3b, v146
	v_mul_f32_e32 v155, 0xbfb8aa3b, v147
	v_exp_f32_e32 v152, v152
	v_exp_f32_e32 v153, v153
	v_exp_f32_e32 v154, v154
	v_exp_f32_e32 v155, v155
	v_add_f32_e32 v152, 1.0, v152
	v_add_f32_e32 v153, 1.0, v153
	v_add_f32_e32 v154, 1.0, v154
	v_add_f32_e32 v155, 1.0, v155
	v_rcp_f32_e32 v152, v152
	v_rcp_f32_e32 v153, v153
	v_rcp_f32_e32 v154, v154
	v_rcp_f32_e32 v155, v155
	v_pk_mul_f32 v[144:145], v[144:145], v[152:153]
	v_pk_mul_f32 v[146:147], v[146:147], v[154:155]
	v_pk_mul_f32 v[144:145], v[144:145], v[148:149]
	v_pk_mul_f32 v[146:147], v[146:147], v[150:151]
	v_cvt_pk_bf16_f32 v144, v144, v145
	v_cvt_pk_bf16_f32 v145, v146, v147
	v_mul_f32_e32 v152, 0xbfb8aa3b, v140
	v_mul_f32_e32 v153, 0xbfb8aa3b, v141
	v_mul_f32_e32 v154, 0xbfb8aa3b, v142
	v_mul_f32_e32 v155, 0xbfb8aa3b, v143
	v_exp_f32_e32 v152, v152
	v_exp_f32_e32 v153, v153
	v_exp_f32_e32 v154, v154
	v_exp_f32_e32 v155, v155
	v_add_f32_e32 v152, 1.0, v152
	v_add_f32_e32 v153, 1.0, v153
	v_add_f32_e32 v154, 1.0, v154
	v_add_f32_e32 v155, 1.0, v155
	v_rcp_f32_e32 v152, v152
	v_rcp_f32_e32 v153, v153
	v_rcp_f32_e32 v154, v154
	v_rcp_f32_e32 v155, v155
	v_pk_mul_f32 v[140:141], v[140:141], v[152:153]
	v_pk_mul_f32 v[142:143], v[142:143], v[154:155]
	v_pk_mul_f32 v[140:141], v[140:141], v[136:137]
	v_pk_mul_f32 v[142:143], v[142:143], v[138:139]
	v_cvt_pk_bf16_f32 v146, v140, v141
	v_cvt_pk_bf16_f32 v147, v142, v143
	s_nop 1
	v_permlane16_swap_b32_e32 v144, v146
	v_permlane16_swap_b32_e32 v145, v147
	global_store_dwordx4 v[156:157], v[144:147], off
	v_lshl_add_u64 v[156:157], v[156:157], 0, s[98:99]
	v_mul_f32_e32 v152, 0xbfb8aa3b, v132
	v_mul_f32_e32 v153, 0xbfb8aa3b, v133
	v_mul_f32_e32 v154, 0xbfb8aa3b, v134
	v_mul_f32_e32 v155, 0xbfb8aa3b, v135
	v_exp_f32_e32 v152, v152
	v_exp_f32_e32 v153, v153
	v_exp_f32_e32 v154, v154
	v_exp_f32_e32 v155, v155
	v_add_f32_e32 v152, 1.0, v152
	v_add_f32_e32 v153, 1.0, v153
	v_add_f32_e32 v154, 1.0, v154
	v_add_f32_e32 v155, 1.0, v155
	v_rcp_f32_e32 v152, v152
	v_rcp_f32_e32 v153, v153
	v_rcp_f32_e32 v154, v154
	v_rcp_f32_e32 v155, v155
	v_pk_mul_f32 v[132:133], v[132:133], v[152:153]
	v_pk_mul_f32 v[134:135], v[134:135], v[154:155]
	v_pk_mul_f32 v[132:133], v[132:133], v[128:129]
	v_pk_mul_f32 v[134:135], v[134:135], v[130:131]
	v_cvt_pk_bf16_f32 v132, v132, v133
	v_cvt_pk_bf16_f32 v133, v134, v135
	v_mul_f32_e32 v152, 0xbfb8aa3b, v124
	v_mul_f32_e32 v153, 0xbfb8aa3b, v125
	v_mul_f32_e32 v154, 0xbfb8aa3b, v126
	v_mul_f32_e32 v155, 0xbfb8aa3b, v127
	v_exp_f32_e32 v152, v152
	v_exp_f32_e32 v153, v153
	v_exp_f32_e32 v154, v154
	v_exp_f32_e32 v155, v155
	v_add_f32_e32 v152, 1.0, v152
	v_add_f32_e32 v153, 1.0, v153
	v_add_f32_e32 v154, 1.0, v154
	v_add_f32_e32 v155, 1.0, v155
	v_rcp_f32_e32 v152, v152
	v_rcp_f32_e32 v153, v153
	v_rcp_f32_e32 v154, v154
	v_rcp_f32_e32 v155, v155
	v_pk_mul_f32 v[124:125], v[124:125], v[152:153]
	v_pk_mul_f32 v[126:127], v[126:127], v[154:155]
	v_pk_mul_f32 v[124:125], v[124:125], v[120:121]
	v_pk_mul_f32 v[126:127], v[126:127], v[122:123]
	v_cvt_pk_bf16_f32 v134, v124, v125
	v_cvt_pk_bf16_f32 v135, v126, v127
	s_nop 1
	v_permlane16_swap_b32_e32 v132, v134
	v_permlane16_swap_b32_e32 v133, v135
	global_store_dwordx4 v[156:157], v[132:135], off
	v_lshl_add_u64 v[156:157], v[156:157], 0, s[98:99]
	v_mul_f32_e32 v152, 0xbfb8aa3b, v112
	v_mul_f32_e32 v153, 0xbfb8aa3b, v113
	v_mul_f32_e32 v154, 0xbfb8aa3b, v114
	v_mul_f32_e32 v155, 0xbfb8aa3b, v115
	v_exp_f32_e32 v152, v152
	v_exp_f32_e32 v153, v153
	v_exp_f32_e32 v154, v154
	v_exp_f32_e32 v155, v155
	v_add_f32_e32 v152, 1.0, v152
	v_add_f32_e32 v153, 1.0, v153
	v_add_f32_e32 v154, 1.0, v154
	v_add_f32_e32 v155, 1.0, v155
	v_rcp_f32_e32 v152, v152
	v_rcp_f32_e32 v153, v153
	v_rcp_f32_e32 v154, v154
	v_rcp_f32_e32 v155, v155
	v_pk_mul_f32 v[112:113], v[112:113], v[152:153]
	v_pk_mul_f32 v[114:115], v[114:115], v[154:155]
	v_pk_mul_f32 v[112:113], v[112:113], v[116:117]
	v_pk_mul_f32 v[114:115], v[114:115], v[118:119]
	v_cvt_pk_bf16_f32 v112, v112, v113
	v_cvt_pk_bf16_f32 v113, v114, v115
	v_mul_f32_e32 v152, 0xbfb8aa3b, v108
	v_mul_f32_e32 v153, 0xbfb8aa3b, v109
	v_mul_f32_e32 v154, 0xbfb8aa3b, v110
	v_mul_f32_e32 v155, 0xbfb8aa3b, v111
	v_exp_f32_e32 v152, v152
	v_exp_f32_e32 v153, v153
	v_exp_f32_e32 v154, v154
	v_exp_f32_e32 v155, v155
	v_add_f32_e32 v152, 1.0, v152
	v_add_f32_e32 v153, 1.0, v153
	v_add_f32_e32 v154, 1.0, v154
	v_add_f32_e32 v155, 1.0, v155
	v_rcp_f32_e32 v152, v152
	v_rcp_f32_e32 v153, v153
	v_rcp_f32_e32 v154, v154
	v_rcp_f32_e32 v155, v155
	v_pk_mul_f32 v[108:109], v[108:109], v[152:153]
	v_pk_mul_f32 v[110:111], v[110:111], v[154:155]
; __device__ __forceinline__ float siluf_(float x) { return x * __builtin_amdgcn_rcpf(1.0f + __builtin_amdgcn_exp2f(-1.4426950408889634f * x)); }
;     ...
;     } else if constexpr (EPI == EPI_SWIGLU) {
;       u16* Gp = (u16*)(ws + OFF_G);
; #pragma unroll
;       for (int m = 0; m < MT; ++m)
; #pragma unroll
;         for (int h = 0; h < 2; ++h) {
;           u32x2 pk;
;           pk.x = pack2(siluf_(acc[m][h][0]) * acc[m][2 + h][0], siluf_(acc[m][h][1]) * acc[m][2 + h][1]);
;           pk.y = pack2(siluf_(acc[m][h][2]) * acc[m][2 + h][2], siluf_(acc[m][h][3]) * acc[m][2 + h][3]);
;           *(u32x2*)(Gp + (size_t)(rbase + m * 16) * DFF + pn * 128 + wc * 32 + h * 16 + fq * 4) = pk;
;         }
	v_pk_mul_f32 v[108:109], v[108:109], v[104:105]
	v_pk_mul_f32 v[110:111], v[110:111], v[106:107]
	v_cvt_pk_bf16_f32 v114, v108, v109
	v_cvt_pk_bf16_f32 v115, v110, v111
	s_nop 1
	v_permlane16_swap_b32_e32 v112, v114
	v_permlane16_swap_b32_e32 v113, v115
	global_store_dwordx4 v[156:157], v[112:115], off
	v_lshl_add_u64 v[156:157], v[156:157], 0, s[98:99]
	v_mul_f32_e32 v152, 0xbfb8aa3b, v100
	v_mul_f32_e32 v153, 0xbfb8aa3b, v101
	v_mul_f32_e32 v154, 0xbfb8aa3b, v102
	v_mul_f32_e32 v155, 0xbfb8aa3b, v103
	v_exp_f32_e32 v152, v152
	v_exp_f32_e32 v153, v153
	v_exp_f32_e32 v154, v154
	v_exp_f32_e32 v155, v155
	v_add_f32_e32 v152, 1.0, v152
	v_add_f32_e32 v153, 1.0, v153
	v_add_f32_e32 v154, 1.0, v154
	v_add_f32_e32 v155, 1.0, v155
	v_rcp_f32_e32 v152, v152
	v_rcp_f32_e32 v153, v153
	v_rcp_f32_e32 v154, v154
	v_rcp_f32_e32 v155, v155
	v_pk_mul_f32 v[100:101], v[100:101], v[152:153]
	v_pk_mul_f32 v[102:103], v[102:103], v[154:155]
	v_pk_mul_f32 v[100:101], v[100:101], v[96:97]
	v_pk_mul_f32 v[102:103], v[102:103], v[98:99]
	v_cvt_pk_bf16_f32 v100, v100, v101
	v_cvt_pk_bf16_f32 v101, v102, v103
	v_mul_f32_e32 v152, 0xbfb8aa3b, v92
	v_mul_f32_e32 v153, 0xbfb8aa3b, v93
	v_mul_f32_e32 v154, 0xbfb8aa3b, v94
	v_mul_f32_e32 v155, 0xbfb8aa3b, v95
	v_exp_f32_e32 v152, v152
	v_exp_f32_e32 v153, v153
	v_exp_f32_e32 v154, v154
	v_exp_f32_e32 v155, v155
	v_add_f32_e32 v152, 1.0, v152
	v_add_f32_e32 v153, 1.0, v153
	v_add_f32_e32 v154, 1.0, v154
	v_add_f32_e32 v155, 1.0, v155
	v_rcp_f32_e32 v152, v152
	v_rcp_f32_e32 v153, v153
	v_rcp_f32_e32 v154, v154
	v_rcp_f32_e32 v155, v155
	v_pk_mul_f32 v[92:93], v[92:93], v[152:153]
	v_pk_mul_f32 v[94:95], v[94:95], v[154:155]
	v_pk_mul_f32 v[92:93], v[92:93], v[88:89]
	v_pk_mul_f32 v[94:95], v[94:95], v[90:91]
	v_cvt_pk_bf16_f32 v102, v92, v93
	v_cvt_pk_bf16_f32 v103, v94, v95
	s_nop 1
	v_permlane16_swap_b32_e32 v100, v102
	v_permlane16_swap_b32_e32 v101, v103
	global_store_dwordx4 v[156:157], v[100:103], off
	v_lshl_add_u64 v[156:157], v[156:157], 0, s[98:99]
	v_mul_f32_e32 v152, 0xbfb8aa3b, v80
	v_mul_f32_e32 v153, 0xbfb8aa3b, v81
	v_mul_f32_e32 v154, 0xbfb8aa3b, v82
	v_mul_f32_e32 v155, 0xbfb8aa3b, v83
	v_exp_f32_e32 v152, v152
	v_exp_f32_e32 v153, v153
	v_exp_f32_e32 v154, v154
	v_exp_f32_e32 v155, v155
	v_add_f32_e32 v152, 1.0, v152
	v_add_f32_e32 v153, 1.0, v153
	v_add_f32_e32 v154, 1.0, v154
	v_add_f32_e32 v155, 1.0, v155
	v_rcp_f32_e32 v152, v152
	v_rcp_f32_e32 v153, v153
	v_rcp_f32_e32 v154, v154
	v_rcp_f32_e32 v155, v155
	v_pk_mul_f32 v[80:81], v[80:81], v[152:153]
	v_pk_mul_f32 v[82:83], v[82:83], v[154:155]
	v_pk_mul_f32 v[80:81], v[80:81], v[84:85]
	v_pk_mul_f32 v[82:83], v[82:83], v[86:87]
	v_cvt_pk_bf16_f32 v80, v80, v81
	v_cvt_pk_bf16_f32 v81, v82, v83
	v_mul_f32_e32 v152, 0xbfb8aa3b, v76
	v_mul_f32_e32 v153, 0xbfb8aa3b, v77
	v_mul_f32_e32 v154, 0xbfb8aa3b, v78
	v_mul_f32_e32 v155, 0xbfb8aa3b, v79
	v_exp_f32_e32 v152, v152
	v_exp_f32_e32 v153, v153
	v_exp_f32_e32 v154, v154
	v_exp_f32_e32 v155, v155
	v_add_f32_e32 v152, 1.0, v152
	v_add_f32_e32 v153, 1.0, v153
	v_add_f32_e32 v154, 1.0, v154
	v_add_f32_e32 v155, 1.0, v155
	v_rcp_f32_e32 v152, v152
	v_rcp_f32_e32 v153, v153
	v_rcp_f32_e32 v154, v154
	v_rcp_f32_e32 v155, v155
	v_pk_mul_f32 v[76:77], v[76:77], v[152:153]
	v_pk_mul_f32 v[78:79], v[78:79], v[154:155]
	v_pk_mul_f32 v[76:77], v[76:77], v[72:73]
	v_pk_mul_f32 v[78:79], v[78:79], v[74:75]
	v_cvt_pk_bf16_f32 v82, v76, v77
	v_cvt_pk_bf16_f32 v83, v78, v79
	s_nop 1
	v_permlane16_swap_b32_e32 v80, v82
	v_permlane16_swap_b32_e32 v81, v83
	global_store_dwordx4 v[156:157], v[80:83], off
	v_lshl_add_u64 v[156:157], v[156:157], 0, s[98:99]
	v_mul_f32_e32 v152, 0xbfb8aa3b, v68
	v_mul_f32_e32 v153, 0xbfb8aa3b, v69
	v_mul_f32_e32 v154, 0xbfb8aa3b, v70
	v_mul_f32_e32 v155, 0xbfb8aa3b, v71
	v_exp_f32_e32 v152, v152
	v_exp_f32_e32 v153, v153
	v_exp_f32_e32 v154, v154
	v_exp_f32_e32 v155, v155
	v_add_f32_e32 v152, 1.0, v152
	v_add_f32_e32 v153, 1.0, v153
	v_add_f32_e32 v154, 1.0, v154
	v_add_f32_e32 v155, 1.0, v155
	v_rcp_f32_e32 v152, v152
	v_rcp_f32_e32 v153, v153
	v_rcp_f32_e32 v154, v154
	v_rcp_f32_e32 v155, v155
	v_pk_mul_f32 v[68:69], v[68:69], v[152:153]
	v_pk_mul_f32 v[70:71], v[70:71], v[154:155]
	v_pk_mul_f32 v[68:69], v[68:69], v[64:65]
	v_pk_mul_f32 v[70:71], v[70:71], v[66:67]
	v_cvt_pk_bf16_f32 v68, v68, v69
	v_cvt_pk_bf16_f32 v69, v70, v71
	v_mul_f32_e32 v152, 0xbfb8aa3b, v60
	v_mul_f32_e32 v153, 0xbfb8aa3b, v61
; __device__ __forceinline__ float siluf_(float x) { return x * __builtin_amdgcn_rcpf(1.0f + __builtin_amdgcn_exp2f(-1.4426950408889634f * x)); }
; #define WAIT_V(n) asm volatile("s_waitcnt vmcnt(%0)" ::"n"(n) : "memory")
;     ...
;           if (q == 2 * NP - 1) {
;             WAIT_V(0);
;             __syncthreads();
;             if (more) {
;               if constexpr (BDBL) {
; #pragma unroll
;                 for (int n = 0; n < 4; ++n) Bq[0][n] = *(const bf16x8*)(sn + boff + (n * 2 + 0) * 1024);
;               }
; #pragma unroll
;               for (int i = 0; i < 2; ++i) Aq[0][i] = *(const bf16x8*)(sn + aoff + (i * 2 + 0) * 1024);
;             }
;     ...
;     } else if constexpr (EPI == EPI_SWIGLU) {
;       u16* Gp = (u16*)(ws + OFF_G);
; #pragma unroll
;       for (int m = 0; m < MT; ++m)
; #pragma unroll
;         for (int h = 0; h < 2; ++h) {
;           u32x2 pk;
;           pk.x = pack2(siluf_(acc[m][h][0]) * acc[m][2 + h][0], siluf_(acc[m][h][1]) * acc[m][2 + h][1]);
;           pk.y = pack2(siluf_(acc[m][h][2]) * acc[m][2 + h][2], siluf_(acc[m][h][3]) * acc[m][2 + h][3]);
;           *(u32x2*)(Gp + (size_t)(rbase + m * 16) * DFF + pn * 128 + wc * 32 + h * 16 + fq * 4) = pk;
;         }
	v_mul_f32_e32 v154, 0xbfb8aa3b, v62
	v_mul_f32_e32 v155, 0xbfb8aa3b, v63
	v_exp_f32_e32 v152, v152
	v_exp_f32_e32 v153, v153
	v_exp_f32_e32 v154, v154
	v_exp_f32_e32 v155, v155
	v_add_f32_e32 v152, 1.0, v152
	v_add_f32_e32 v153, 1.0, v153
	v_add_f32_e32 v154, 1.0, v154
	v_add_f32_e32 v155, 1.0, v155
	v_rcp_f32_e32 v152, v152
	v_rcp_f32_e32 v153, v153
	v_rcp_f32_e32 v154, v154
	v_rcp_f32_e32 v155, v155
	v_pk_mul_f32 v[60:61], v[60:61], v[152:153]
	v_pk_mul_f32 v[62:63], v[62:63], v[154:155]
	v_pk_mul_f32 v[60:61], v[60:61], v[56:57]
	v_pk_mul_f32 v[62:63], v[62:63], v[58:59]
	v_cvt_pk_bf16_f32 v70, v60, v61
	v_cvt_pk_bf16_f32 v71, v62, v63
	s_nop 1
	v_permlane16_swap_b32_e32 v68, v70
	v_permlane16_swap_b32_e32 v69, v71
	global_store_dwordx4 v[156:157], v[68:71], off
	v_lshl_add_u64 v[156:157], v[156:157], 0, s[98:99]
	v_mul_f32_e32 v152, 0xbfb8aa3b, v48
	v_mul_f32_e32 v153, 0xbfb8aa3b, v49
	v_mul_f32_e32 v154, 0xbfb8aa3b, v50
	v_mul_f32_e32 v155, 0xbfb8aa3b, v51
	v_exp_f32_e32 v152, v152
	v_exp_f32_e32 v153, v153
	v_exp_f32_e32 v154, v154
	v_exp_f32_e32 v155, v155
	v_add_f32_e32 v152, 1.0, v152
	v_add_f32_e32 v153, 1.0, v153
	v_add_f32_e32 v154, 1.0, v154
	v_add_f32_e32 v155, 1.0, v155
	v_rcp_f32_e32 v152, v152
	v_rcp_f32_e32 v153, v153
	v_rcp_f32_e32 v154, v154
	v_rcp_f32_e32 v155, v155
	v_pk_mul_f32 v[48:49], v[48:49], v[152:153]
	v_pk_mul_f32 v[50:51], v[50:51], v[154:155]
	v_pk_mul_f32 v[48:49], v[48:49], v[52:53]
	v_pk_mul_f32 v[50:51], v[50:51], v[54:55]
	v_cvt_pk_bf16_f32 v48, v48, v49
	v_cvt_pk_bf16_f32 v49, v50, v51
	v_mul_f32_e32 v152, 0xbfb8aa3b, v44
	v_mul_f32_e32 v153, 0xbfb8aa3b, v45
	v_mul_f32_e32 v154, 0xbfb8aa3b, v46
	v_mul_f32_e32 v155, 0xbfb8aa3b, v47
	v_exp_f32_e32 v152, v152
	v_exp_f32_e32 v153, v153
	v_exp_f32_e32 v154, v154
	v_exp_f32_e32 v155, v155
	v_add_f32_e32 v152, 1.0, v152
	v_add_f32_e32 v153, 1.0, v153
	v_add_f32_e32 v154, 1.0, v154
	v_add_f32_e32 v155, 1.0, v155
	v_rcp_f32_e32 v152, v152
	v_rcp_f32_e32 v153, v153
	v_rcp_f32_e32 v154, v154
	v_rcp_f32_e32 v155, v155
	v_pk_mul_f32 v[44:45], v[44:45], v[152:153]
	v_pk_mul_f32 v[46:47], v[46:47], v[154:155]
	v_pk_mul_f32 v[44:45], v[44:45], v[40:41]
	v_pk_mul_f32 v[46:47], v[46:47], v[42:43]
	v_cvt_pk_bf16_f32 v50, v44, v45
	v_cvt_pk_bf16_f32 v51, v46, v47
	s_nop 1
	v_permlane16_swap_b32_e32 v48, v50
	v_permlane16_swap_b32_e32 v49, v51
	global_store_dwordx4 v[156:157], v[48:51], off
	v_lshl_add_u64 v[156:157], v[156:157], 0, s[98:99]
	v_mul_f32_e32 v152, 0xbfb8aa3b, v36
	v_mul_f32_e32 v153, 0xbfb8aa3b, v37
	v_mul_f32_e32 v154, 0xbfb8aa3b, v38
	v_mul_f32_e32 v155, 0xbfb8aa3b, v39
	v_exp_f32_e32 v152, v152
	v_exp_f32_e32 v153, v153
	v_exp_f32_e32 v154, v154
	v_exp_f32_e32 v155, v155
	v_add_f32_e32 v152, 1.0, v152
	v_add_f32_e32 v153, 1.0, v153
	v_add_f32_e32 v154, 1.0, v154
	v_add_f32_e32 v155, 1.0, v155
	v_rcp_f32_e32 v152, v152
	v_rcp_f32_e32 v153, v153
	v_rcp_f32_e32 v154, v154
	v_rcp_f32_e32 v155, v155
	v_pk_mul_f32 v[36:37], v[36:37], v[152:153]
	v_pk_mul_f32 v[38:39], v[38:39], v[154:155]
	v_pk_mul_f32 v[36:37], v[36:37], v[32:33]
	v_pk_mul_f32 v[38:39], v[38:39], v[34:35]
	v_cvt_pk_bf16_f32 v36, v36, v37
	v_cvt_pk_bf16_f32 v37, v38, v39
	v_mul_f32_e32 v152, 0xbfb8aa3b, v28
	v_mul_f32_e32 v153, 0xbfb8aa3b, v29
	v_mul_f32_e32 v154, 0xbfb8aa3b, v30
	v_mul_f32_e32 v155, 0xbfb8aa3b, v31
	v_exp_f32_e32 v152, v152
	v_exp_f32_e32 v153, v153
	v_exp_f32_e32 v154, v154
	v_exp_f32_e32 v155, v155
	v_add_f32_e32 v152, 1.0, v152
	v_add_f32_e32 v153, 1.0, v153
	v_add_f32_e32 v154, 1.0, v154
	v_add_f32_e32 v155, 1.0, v155
	v_rcp_f32_e32 v152, v152
	v_rcp_f32_e32 v153, v153
	v_rcp_f32_e32 v154, v154
	v_rcp_f32_e32 v155, v155
	v_pk_mul_f32 v[28:29], v[28:29], v[152:153]
	v_pk_mul_f32 v[30:31], v[30:31], v[154:155]
	v_pk_mul_f32 v[28:29], v[28:29], v[24:25]
	v_pk_mul_f32 v[30:31], v[30:31], v[26:27]
	v_cvt_pk_bf16_f32 v38, v28, v29
	v_cvt_pk_bf16_f32 v39, v30, v31
	s_nop 1
	v_permlane16_swap_b32_e32 v36, v38
	v_permlane16_swap_b32_e32 v37, v39
	global_store_dwordx4 v[156:157], v[36:39], off
	s_waitcnt vmcnt(8)
	s_barrier
	s_and_b64 vcc, exec, s[12:13]
	s_mov_b32 s50, s23
	s_mov_b32 s25, s21
	s_mov_b64 s[16:17], s[6:7]
	s_mov_b64 s[0:1], s[10:11]
	s_cbranch_vccnz .LBB0_191
	ds_read_b128 v[12:15], v221 offset:32768
	ds_read_b128 v[8:11], v221 offset:34816
	ds_read_b128 v[4:7], v221 offset:36864
	ds_read_b128 v[0:3], v221 offset:38912
	ds_read_b128 v[20:23], v220
	ds_read_b128 v[16:19], v220 offset:2048

; #define WAIT_V(n) asm volatile("s_waitcnt vmcnt(%0)" ::"n"(n) : "memory")
;     ...
;       for (int ks = 0; ks < 2; ++ks) {
; #pragma unroll
;         for (int p = 0; p < NP; ++p) {
;           const int q = ks * NP + p;
;           acc[p * 2][0] = __builtin_amdgcn_mfma_f32_16x16x32_bf16(Bq[BDBL ? ks : 0][0], Aq[q & 1][0], acc[p * 2][0], 0, 0, 0);
;           __builtin_amdgcn_sched_barrier(0);
;           if (q == 2 * NP - 1) {
;             WAIT_V(0);
;             __syncthreads();
;             if (more) {
;               if constexpr (BDBL) {
; #pragma unroll
;                 for (int n = 0; n < 4; ++n) Bq[0][n] = *(const bf16x8*)(sn + boff + (n * 2 + 0) * 1024);
;               }
; #pragma unroll
;               for (int i = 0; i < 2; ++i) Aq[0][i] = *(const bf16x8*)(sn + aoff + (i * 2 + 0) * 1024);
;             }
;           } else if (p + 1 < NP) {
; #pragma unroll
;             for (int i = 0; i < 2; ++i) Aq[(q + 1) & 1][i] = *(const bf16x8*)(sa + aoff + (((p + 1) * 2 + i) * 2 + ks) * 1024);
;           } else {
;             if constexpr (BDBL) {
; #pragma unroll
;               for (int n = 0; n < 4; ++n) Bq[1][n] = *(const bf16x8*)(sa + boff + (n * 2 + 1) * 1024);
;             }
; #pragma unroll
;             for (int i = 0; i < 2; ++i) Aq[(q + 1) & 1][i] = *(const bf16x8*)(sa + aoff + (i * 2 + 1) * 1024);
;           }
;           __builtin_amdgcn_sched_barrier(0);
; #pragma unroll
;           for (int i = 0; i < 2; ++i)
; #pragma unroll
;             for (int n = 0; n < 4; ++n)
;               if (i + n > 0)
;                 acc[p * 2 + i][n] = __builtin_amdgcn_mfma_f32_16x16x32_bf16(Bq[BDBL ? ks : 0][n], Aq[q & 1][i], acc[p * 2 + i][n], 0, 0, 0);
;           __builtin_amdgcn_sched_barrier(0);
;           if (q == GLDS_AT) {
;             if (t + 1 < nt) GLDS_STAGE(cur ^ 1, t + 1, Ab, Bb);
;             else if (nitem < ntiles) GLDS_STAGE(0, 0, nAb, nBb);
;             __builtin_amdgcn_sched_barrier(0);
;           }
.LBB0_189:
	s_waitcnt lgkmcnt(0)
	v_mfma_f32_16x16x32_bf16 v[144:147], v[152:155], v[76:79], v[148:151]
	ds_read_b128 v[28:31], v226 offset:5120
	ds_read_b128 v[44:47], v226 offset:7168
	v_mfma_f32_16x16x32_bf16 v[140:143], v[156:159], v[76:79], v[176:179]
	v_mfma_f32_16x16x32_bf16 v[148:151], v[160:163], v[76:79], v[180:183]
	v_mfma_f32_16x16x32_bf16 v[136:139], v[164:167], v[76:79], v[20:23]
	v_mfma_f32_16x16x32_bf16 v[132:135], v[152:155], v[60:63], v[132:135]
	v_mfma_f32_16x16x32_bf16 v[124:127], v[156:159], v[60:63], v[128:131]
	v_mfma_f32_16x16x32_bf16 v[128:131], v[160:163], v[60:63], v[184:187]
	v_mfma_f32_16x16x32_bf16 v[120:123], v[164:167], v[60:63], v[16:19]
	s_waitcnt lgkmcnt(1)
	v_mfma_f32_16x16x32_bf16 v[112:115], v[152:155], v[28:31], v[116:119]
	ds_read_b128 v[20:23], v226 offset:9216
	ds_read_b128 v[16:19], v226 offset:11264
	v_mfma_f32_16x16x32_bf16 v[108:111], v[156:159], v[28:31], v[188:191]
	v_mfma_f32_16x16x32_bf16 v[116:119], v[160:163], v[28:31], v[192:195]
	v_mfma_f32_16x16x32_bf16 v[104:107], v[164:167], v[28:31], v[104:107]
	s_waitcnt lgkmcnt(2)
	v_mfma_f32_16x16x32_bf16 v[100:103], v[152:155], v[44:47], v[100:103]
	v_mfma_f32_16x16x32_bf16 v[92:95], v[156:159], v[44:47], v[96:99]
	v_mfma_f32_16x16x32_bf16 v[96:99], v[160:163], v[44:47], v[196:199]
	v_mfma_f32_16x16x32_bf16 v[88:91], v[164:167], v[44:47], v[88:91]
	s_waitcnt lgkmcnt(1)
	v_mfma_f32_16x16x32_bf16 v[80:83], v[152:155], v[20:23], v[84:87]
	ds_read_b128 v[28:31], v226 offset:13312
	ds_read_b128 v[176:179], v226 offset:15360
	v_mfma_f32_16x16x32_bf16 v[76:79], v[156:159], v[20:23], v[200:203]
	v_mfma_f32_16x16x32_bf16 v[84:87], v[160:163], v[20:23], v[204:207]
	v_mfma_f32_16x16x32_bf16 v[72:75], v[164:167], v[20:23], v[72:75]
	s_waitcnt lgkmcnt(2)
	v_mfma_f32_16x16x32_bf16 v[68:71], v[152:155], v[16:19], v[68:71]
	v_mfma_f32_16x16x32_bf16 v[60:63], v[156:159], v[16:19], v[64:67]
	v_mfma_f32_16x16x32_bf16 v[64:67], v[160:163], v[16:19], v[208:211]
	v_mfma_f32_16x16x32_bf16 v[56:59], v[164:167], v[16:19], v[56:59]
	s_waitcnt lgkmcnt(1)
	v_mfma_f32_16x16x32_bf16 v[48:51], v[152:155], v[28:31], v[212:215]
	s_waitcnt lgkmcnt(0)
	s_branch .LBB0_182
